# GEMM_in main loop: first fragment ds_reads issued right after the barrier, before the LDS-DMA issues
# baseline (speedup 1.0000x reference)
; DI f32x16 mfma32(bf16x8 a, bf16x8 b, f32x16 c) { return __builtin_amdgcn_mfma_f32_32x32x16_bf16(a, b, c, 0, 0, 0); }
; #define RAW_BARRIER() do { asm volatile("s_waitcnt lgkmcnt(0)" ::: "memory"); __builtin_amdgcn_s_barrier(); } while (0)
; DI void gemm_tile(const Params& p, const GemmJob& j, int mt, int nt, char* smem) {
;     ...
;   for (int kt = 0; kt < nk; ++kt) {
;     if (kt + 1 < nk) asm volatile("s_waitcnt vmcnt(6)" ::: "memory"); else asm volatile("s_waitcnt vmcnt(0)" ::: "memory");
;     RAW_BARRIER();
;     if (kt + 2 < nk) glds(kt + 2, st2);
;     const char* sb = smem + st * GSTAGE;
; #pragma unroll
;     for (int ks = 0; ks < 2; ++ks) {
;       const int off = ks ? (o0 ^ 32) : o0;
;       bf16x8 wf[2], xf[4];
; #pragma unroll
;       for (int a = 0; a < 2; ++a) wf[a] = *(const bf16x8*)(sb + (64 * wn + 32 * a + r) * 64 + off);
; #pragma unroll
;       for (int b = 0; b < 4; ++b) xf[b] = *(const bf16x8*)(sb + 8192 + (128 * wt + 32 * b + r) * 64 + off);
; #pragma unroll
;       for (int a = 0; a < 2; ++a)
; #pragma unroll
;         for (int b = 0; b < 4; ++b) acc[a][b] = mfma32(wf[a], xf[b], acc[a][b]);
;     }
;     st = (st == 2) ? 0 : st + 1; st2 = (st2 == 2) ? 0 : st2 + 1;
;   }
.LBB0_103:
	s_add_i32 s37, s63, s33
	v_lshl_add_u64 v[232:233], v[232:233], 0, v[0:1]
	s_mov_b32 m0, s37
	v_lshl_add_u64 v[134:135], v[134:135], 0, 64
	global_load_lds_dwordx4 v[232:233], off
	v_lshl_add_u64 v[232:233], v[138:139], 0, s[8:9]
	v_lshl_add_u64 v[234:235], v[232:233], 0, s[92:93]
	s_add_i32 m0, s36, 0x2000
	s_add_i32 s36, s63, s55
	global_load_lds_dwordx4 v[234:235], off
	v_lshl_add_u64 v[234:235], v[140:141], 0, s[8:9]
	s_add_i32 m0, s37, 0x2000
	v_lshl_add_u64 v[136:137], v[136:137], 0, 64
	global_load_lds_dwordx4 v[234:235], off
	v_lshl_add_u64 v[234:235], v[232:233], 0, s[84:85]
	s_add_i32 m0, s36, 0x2000
	s_add_i32 s36, s63, s58
	global_load_lds_dwordx4 v[234:235], off
	v_lshl_add_u64 v[232:233], v[232:233], 0, s[52:53]
	s_add_i32 m0, s36, 0x2000
	s_nop 0
	global_load_lds_dwordx4 v[232:233], off
	s_waitcnt lgkmcnt(0)
	v_mfma_f32_32x32x16_bf16 v[114:129], v[152:155], v[156:159], v[114:129]
	v_add_u32_e32 v142, s100, v150
	s_add_i32 s36, s11, 1
	s_cmp_lg_u32 s11, 2
	s_cselect_b32 s11, s36, 0
	s_add_i32 s36, s70, 1
	s_cmp_lg_u32 s70, 2
	s_cselect_b32 s70, s36, 0
	v_mfma_f32_32x32x16_bf16 v[82:97], v[152:155], v[160:163], v[82:97]
	s_add_u32 s8, s8, 0x200000
	s_addc_u32 s9, s9, 0
	s_add_i32 s62, s62, 1
	s_cmp_eq_u32 s8, 0x3c00000
	v_mfma_f32_32x32x16_bf16 v[50:65], v[152:155], v[180:183], v[50:65]
	v_mfma_f32_32x32x16_bf16 v[18:33], v[152:155], v[184:187], v[18:33]
	ds_read_b128 v[152:155], v143 offset:2048
	v_add_u32_e32 v143, v142, v149
	v_add_u32_e32 v142, v142, v148
	s_waitcnt lgkmcnt(0)
	v_mfma_f32_32x32x16_bf16 v[98:113], v[152:155], v[156:159], v[98:113]
	ds_read_b128 v[156:159], v142 offset:8192
	v_mfma_f32_32x32x16_bf16 v[66:81], v[152:155], v[160:163], v[66:81]
	ds_read_b128 v[160:163], v142 offset:10240
	v_mfma_f32_32x32x16_bf16 v[34:49], v[152:155], v[180:183], v[34:49]
	ds_read_b128 v[180:183], v142 offset:12288
	v_mfma_f32_32x32x16_bf16 v[2:17], v[152:155], v[184:187], v[2:17]
	ds_read_b128 v[152:155], v143
	ds_read_b128 v[184:187], v142 offset:14336
	s_waitcnt lgkmcnt(0)
	v_mfma_f32_32x32x16_bf16 v[114:129], v[152:155], v[156:159], v[114:129]
	v_mfma_f32_32x32x16_bf16 v[82:97], v[152:155], v[160:163], v[82:97]
	v_mfma_f32_32x32x16_bf16 v[50:65], v[152:155], v[180:183], v[50:65]
	v_mfma_f32_32x32x16_bf16 v[18:33], v[152:155], v[184:187], v[18:33]
	ds_read_b128 v[152:155], v143 offset:2048
	s_waitcnt lgkmcnt(0)
	v_mfma_f32_32x32x16_bf16 v[98:113], v[152:155], v[156:159], v[98:113]
	v_mfma_f32_32x32x16_bf16 v[66:81], v[152:155], v[160:163], v[66:81]
	v_mfma_f32_32x32x16_bf16 v[34:49], v[152:155], v[180:183], v[34:49]
	v_mfma_f32_32x32x16_bf16 v[2:17], v[152:155], v[184:187], v[2:17]
	s_cbranch_scc1 .LBB0_108
.LBB0_104:
	s_waitcnt vmcnt(6)
	s_waitcnt lgkmcnt(0)
	s_add_i32 s37, s62, 2
	s_and_b64 vcc, exec, s[6:7]
	s_mul_i32 s38, s37, s3
	v_mov_b64_e32 v[232:233], v[134:135]
	s_mul_i32 s100, s11, 0x6000
	v_add_u32_e32 v142, s100, v147
	v_add_u32_e32 v143, v142, v149
	v_add_u32_e32 v142, v142, v148
	s_barrier
	ds_read_b128 v[152:155], v143
	ds_read_b128 v[156:159], v142 offset:8192
	ds_read_b128 v[160:163], v142 offset:10240
	ds_read_b128 v[180:183], v142 offset:12288
	ds_read_b128 v[184:187], v142 offset:14336
	s_cbranch_vccnz .LBB0_106
	v_mov_b32_e32 v232, s2
	v_mad_u64_u32 v[232:233], s[40:41], s37, v232, v[130:131]
	v_add_u32_e32 v233, s38, v233
	v_lshlrev_b64 v[232:233], 6, v[232:233]
	v_lshl_add_u64 v[232:233], s[4:5], 0, v[232:233]
.LBB0_106:
	s_mul_i32 s36, s70, 0x6000
	s_add_i32 s63, s36, 0
	s_add_i32 s36, s63, s31
	v_lshl_add_u64 v[232:233], v[232:233], 0, v[0:1]
	s_mov_b32 m0, s36
	s_and_b64 vcc, exec, s[6:7]
	global_load_lds_dwordx4 v[232:233], off
	v_mov_b64_e32 v[232:233], v[136:137]
	s_cbranch_vccnz .LBB0_103
	v_mov_b32_e32 v232, s2
	v_mad_u64_u32 v[232:233], s[40:41], s37, v232, v[132:133]
	v_add_u32_e32 v233, s38, v233
	v_lshlrev_b64 v[232:233], 6, v[232:233]
	v_lshl_add_u64 v[232:233], s[4:5], 0, v[232:233]
	s_branch .LBB0_103

; __global__ void __launch_bounds__(256, 2) mega_kernel(Params p) {
;   extern __shared__ __attribute__((aligned(16))) char smem[];
	.amdhsa_kernel _Z11mega_kernel6Params
		.amdhsa_group_segment_fixed_size 0
		.amdhsa_private_segment_fixed_size 0
		.amdhsa_kernarg_size 2784
		.amdhsa_user_sgpr_count 2
		.amdhsa_user_sgpr_dispatch_ptr 0
		.amdhsa_user_sgpr_queue_ptr 0
		.amdhsa_user_sgpr_kernarg_segment_ptr 1
		.amdhsa_user_sgpr_dispatch_id 0
		.amdhsa_user_sgpr_kernarg_preload_length 0
		.amdhsa_user_sgpr_kernarg_preload_offset 0
		.amdhsa_user_sgpr_private_segment_size 0
		.amdhsa_uses_dynamic_stack 0
		.amdhsa_enable_private_segment 0
		.amdhsa_system_sgpr_workgroup_id_x 1
		.amdhsa_system_sgpr_workgroup_id_y 0
		.amdhsa_system_sgpr_workgroup_id_z 0
		.amdhsa_system_sgpr_workgroup_info 0
		.amdhsa_system_vgpr_workitem_id 2
		.amdhsa_next_free_vgpr 236
		.amdhsa_next_free_sgpr 102
		.amdhsa_accum_offset 236
		.amdhsa_reserve_vcc 1
		.amdhsa_float_round_mode_32 0
		.amdhsa_float_round_mode_16_64 0
		.amdhsa_float_denorm_mode_32 3
		.amdhsa_float_denorm_mode_16_64 3
		.amdhsa_dx10_clamp 1
		.amdhsa_ieee_mode 1
		.amdhsa_fp16_overflow 0
		.amdhsa_tg_split 0
		.amdhsa_exception_fp_ieee_invalid_op 0
		.amdhsa_exception_fp_denorm_src 0
		.amdhsa_exception_fp_ieee_div_zero 0
		.amdhsa_exception_fp_ieee_overflow 0
		.amdhsa_exception_fp_ieee_underflow 0
		.amdhsa_exception_fp_ieee_inexact 0
		.amdhsa_exception_int_div_zero 0
	.end_amdhsa_kernel

; __global__ void __launch_bounds__(256, 2) mega_kernel(Params p) {
;   extern __shared__ __attribute__((aligned(16))) char smem[];
amdhsa.kernels:
  - .agpr_count:     0
    .args:
      - .offset:         0
        .size:           2528
        .value_kind:     by_value
      - .offset:         2528
        .size:           4
        .value_kind:     hidden_block_count_x
      - .offset:         2532
        .size:           4
        .value_kind:     hidden_block_count_y
      - .offset:         2536
        .size:           4
        .value_kind:     hidden_block_count_z
      - .offset:         2540
        .size:           2
        .value_kind:     hidden_group_size_x
      - .offset:         2542
        .size:           2
        .value_kind:     hidden_group_size_y
      - .offset:         2544
        .size:           2
        .value_kind:     hidden_group_size_z
      - .offset:         2546
        .size:           2
        .value_kind:     hidden_remainder_x
      - .offset:         2548
        .size:           2
        .value_kind:     hidden_remainder_y
      - .offset:         2550
        .size:           2
        .value_kind:     hidden_remainder_z
      - .offset:         2568
        .size:           8
        .value_kind:     hidden_global_offset_x
      - .offset:         2576
        .size:           8
        .value_kind:     hidden_global_offset_y
      - .offset:         2584
        .size:           8
        .value_kind:     hidden_global_offset_z
      - .offset:         2592
        .size:           2
        .value_kind:     hidden_grid_dims
      - .offset:         2616
        .size:           8
        .value_kind:     hidden_multigrid_sync_arg
      - .offset:         2648
        .size:           4
        .value_kind:     hidden_dynamic_lds_size
    .group_segment_fixed_size: 0
    .kernarg_segment_align: 8
    .kernarg_segment_size: 2784
    .language:       OpenCL C
    .language_version:
      - 2
      - 0
    .max_flat_workgroup_size: 256
    .name:           _Z11mega_kernel6Params
    .private_segment_fixed_size: 0
    .sgpr_count:     108
    .sgpr_spill_count: 128
    .symbol:         _Z11mega_kernel6Params.kd
    .uniform_work_group_size: 1
    .uses_dynamic_stack: false
    .vgpr_count:     236
    .vgpr_spill_count: 0
    .wavefront_size: 64
